# vAA with sc0 sc1 (system-scope write-through) instead of sc1 on the 28 PROJ/G stores
# speedup vs baseline: 1.0060x; 1.0060x over previous
.LBB0_149:
	s_waitcnt lgkmcnt(0)
	v_mov_b64_e32 v[160:161], s[52:53]
	v_mad_i64_i32 v[160:161], s[0:1], v206, s15, v[160:161]
	v_cvt_pk_bf16_f32 v162, v234, v235
	v_cvt_pk_bf16_f32 v163, v166, v167
	v_lshl_add_u64 v[160:161], v[204:205], 1, v[160:161]
	v_mov_b32_e32 v231, v230
	v_cvt_pk_bf16_f32 v164, v236, v237
	v_cvt_pk_bf16_f32 v165, v232, v233
	global_store_dwordx4 v[160:161], v[162:165], off sc0 sc1
	s_and_b64 vcc, exec, s[42:43]
	v_pk_mul_f32 v[166:167], v[144:145], v[230:231]
	v_mov_b32_e32 v162, v230
	v_mov_b32_e32 v163, v230
	v_pk_mul_f32 v[150:151], v[150:151], v[162:163]
	v_pk_mul_f32 v[164:165], v[148:149], v[230:231]
	v_pk_mul_f32 v[162:163], v[146:147], v[162:163]
	s_cbranch_vccnz .LBB0_157
	ds_swizzle_b32 v146, v164 offset:swizzle(SWAP,16)
	ds_swizzle_b32 v144, v166 offset:swizzle(SWAP,16)
	ds_swizzle_b32 v147, v165 offset:swizzle(SWAP,16)
	ds_swizzle_b32 v145, v167 offset:swizzle(SWAP,16)
	ds_swizzle_b32 v232, v150 offset:swizzle(SWAP,16)
	ds_swizzle_b32 v230, v162 offset:swizzle(SWAP,16)
	ds_swizzle_b32 v233, v151 offset:swizzle(SWAP,16)
	ds_swizzle_b32 v231, v163 offset:swizzle(SWAP,16)
	s_and_saveexec_b64 s[0:1], s[46:47]
	s_xor_b64 s[0:1], exec, s[0:1]
	s_cbranch_execz .LBB0_154
	s_and_saveexec_b64 s[4:5], s[44:45]
	s_cbranch_execz .LBB0_153
	s_waitcnt lgkmcnt(0)
	v_pk_mul_f32 v[146:147], v[172:173], v[146:147]
	v_pk_mul_f32 v[148:149], v[174:175], v[232:233]
	v_pk_fma_f32 v[164:165], v[164:165], v[168:169], v[146:147]
	v_pk_mul_f32 v[146:147], v[158:159], v[230:231]
	v_pk_mul_f32 v[144:145], v[156:157], v[144:145]
	v_pk_fma_f32 v[150:151], v[150:151], v[170:171], v[148:149]
	v_pk_fma_f32 v[162:163], v[162:163], v[154:155], v[146:147]
	v_pk_fma_f32 v[166:167], v[166:167], v[152:153], v[144:145]

.LBB0_159:
	s_waitcnt lgkmcnt(0)
	v_cvt_pk_bf16_f32 v144, v164, v165
	v_cvt_pk_bf16_f32 v145, v150, v151
	v_cvt_pk_bf16_f32 v146, v166, v167
	v_cvt_pk_bf16_f32 v147, v162, v163
	global_store_dwordx4 v[160:161], v[144:147], off offset:256 sc0 sc1
	v_pk_mul_f32 v[148:149], v[116:117], v[228:229] op_sel_hi:[1,0]
	s_and_b64 vcc, exec, s[42:43]
	v_pk_mul_f32 v[144:145], v[118:119], v[228:229] op_sel_hi:[1,0]
	v_pk_mul_f32 v[146:147], v[110:111], v[228:229] op_sel_hi:[1,0]
	v_pk_mul_f32 v[150:151], v[108:109], v[228:229] op_sel_hi:[1,0]
	s_cbranch_vccnz .LBB0_167
	ds_swizzle_b32 v116, v148 offset:swizzle(SWAP,16)
	ds_swizzle_b32 v108, v150 offset:swizzle(SWAP,16)
	ds_swizzle_b32 v117, v149 offset:swizzle(SWAP,16)
	ds_swizzle_b32 v109, v151 offset:swizzle(SWAP,16)
	ds_swizzle_b32 v162, v144 offset:swizzle(SWAP,16)
	ds_swizzle_b32 v160, v146 offset:swizzle(SWAP,16)
	ds_swizzle_b32 v163, v145 offset:swizzle(SWAP,16)
	ds_swizzle_b32 v161, v147 offset:swizzle(SWAP,16)
	s_and_saveexec_b64 s[0:1], s[46:47]
	s_xor_b64 s[0:1], exec, s[0:1]
	s_cbranch_execz .LBB0_164
	s_and_saveexec_b64 s[4:5], s[44:45]
	s_cbranch_execz .LBB0_163
	s_waitcnt lgkmcnt(0)
	v_pk_mul_f32 v[110:111], v[126:127], v[162:163]
	v_pk_mul_f32 v[116:117], v[124:125], v[116:117]
	v_pk_fma_f32 v[144:145], v[144:145], v[122:123], v[110:111]
	v_pk_mul_f32 v[110:111], v[114:115], v[160:161]
	v_pk_mul_f32 v[108:109], v[112:113], v[108:109]
	v_pk_fma_f32 v[148:149], v[148:149], v[120:121], v[116:117]
	v_pk_fma_f32 v[146:147], v[146:147], v[106:107], v[110:111]
	v_pk_fma_f32 v[150:151], v[150:151], v[104:105], v[108:109]

.LBB0_169:
	s_waitcnt lgkmcnt(0)
	v_mov_b64_e32 v[108:109], s[52:53]
	v_mad_i64_i32 v[108:109], s[0:1], v224, s15, v[108:109]
	v_mov_b32_e32 v229, v228
	v_cvt_pk_bf16_f32 v116, v148, v149
	v_cvt_pk_bf16_f32 v117, v144, v145
	v_cvt_pk_bf16_f32 v118, v150, v151
	v_cvt_pk_bf16_f32 v119, v146, v147
	v_lshl_add_u64 v[108:109], v[204:205], 1, v[108:109]
	v_mov_b32_e32 v110, v228
	v_mov_b32_e32 v111, v228
	global_store_dwordx4 v[108:109], v[116:119], off sc0 sc1
	v_pk_mul_f32 v[102:103], v[102:103], v[110:111]
	v_pk_mul_f32 v[110:111], v[98:99], v[110:111]
	v_pk_mul_f32 v[116:117], v[100:101], v[228:229]
	s_and_b64 vcc, exec, s[42:43]
	v_pk_mul_f32 v[118:119], v[96:97], v[228:229]
	s_cbranch_vccnz .LBB0_177
	ds_swizzle_b32 v98, v116 offset:swizzle(SWAP,16)
	ds_swizzle_b32 v96, v118 offset:swizzle(SWAP,16)
	ds_swizzle_b32 v99, v117 offset:swizzle(SWAP,16)
	ds_swizzle_b32 v97, v119 offset:swizzle(SWAP,16)
	ds_swizzle_b32 v146, v102 offset:swizzle(SWAP,16)
	ds_swizzle_b32 v144, v110 offset:swizzle(SWAP,16)
	ds_swizzle_b32 v147, v103 offset:swizzle(SWAP,16)
	ds_swizzle_b32 v145, v111 offset:swizzle(SWAP,16)
	s_and_saveexec_b64 s[0:1], s[46:47]
	s_xor_b64 s[0:1], exec, s[0:1]
	s_cbranch_execz .LBB0_174
	s_and_saveexec_b64 s[4:5], s[44:45]
	s_cbranch_execz .LBB0_173
	s_waitcnt lgkmcnt(0)
	v_pk_mul_f32 v[98:99], v[124:125], v[98:99]
	v_pk_mul_f32 v[100:101], v[126:127], v[146:147]
	v_pk_fma_f32 v[116:117], v[116:117], v[120:121], v[98:99]
	v_pk_mul_f32 v[98:99], v[114:115], v[144:145]
	v_pk_mul_f32 v[96:97], v[112:113], v[96:97]
	v_pk_fma_f32 v[102:103], v[102:103], v[122:123], v[100:101]
	v_pk_fma_f32 v[110:111], v[110:111], v[106:107], v[98:99]
	v_pk_fma_f32 v[118:119], v[118:119], v[104:105], v[96:97]

.LBB0_179:
	s_waitcnt lgkmcnt(0)
	v_cvt_pk_bf16_f32 v96, v116, v117
	v_cvt_pk_bf16_f32 v97, v102, v103
	v_cvt_pk_bf16_f32 v98, v118, v119
	v_cvt_pk_bf16_f32 v99, v110, v111
	s_and_b64 vcc, exec, s[42:43]
	global_store_dwordx4 v[108:109], v[96:99], off offset:256 sc0 sc1
	s_cbranch_vccnz .LBB0_181
	s_nop 0
	v_lshlrev_b64 v[96:97], 6, v[220:221]
	v_lshl_add_u64 v[96:97], s[56:57], 0, v[96:97]
	v_lshlrev_b64 v[96:97], 6, v[216:217]
	v_lshl_add_u64 v[108:109], s[56:57], 0, v[96:97]
	s_nop 0
	v_and_b32_e32 v108, 0xff, v206
	v_lshlrev_b32_e32 v108, 6, v108
	v_add_u32_e32 v108, 0x24000, v108
	ds_read_b128 v[148:151], v108 offset:2096
	ds_read_b128 v[164:167], v108 offset:2080
	ds_read_b128 v[144:147], v108 offset:2064
	ds_read_b128 v[160:163], v108 offset:2048
	ds_read_b128 v[100:103], v108 offset:3120
	ds_read_b128 v[116:119], v108 offset:3104
	ds_read_b128 v[96:99], v108 offset:3088
	ds_read_b128 v[108:111], v108 offset:3072

.LBB0_191:
	s_waitcnt lgkmcnt(0)
	v_mov_b64_e32 v[136:137], s[52:53]
	v_mad_i64_i32 v[136:137], s[0:1], v220, s15, v[136:137]
	v_cvt_pk_bf16_f32 v138, v228, v229
	v_cvt_pk_bf16_f32 v139, v142, v143
	v_lshl_add_u64 v[136:137], v[204:205], 1, v[136:137]
	v_mov_b32_e32 v227, v226
	v_cvt_pk_bf16_f32 v140, v230, v231
	v_cvt_pk_bf16_f32 v141, v224, v225
	global_store_dwordx4 v[136:137], v[138:141], off sc0 sc1
	s_and_b64 vcc, exec, s[42:43]
	v_pk_mul_f32 v[142:143], v[128:129], v[226:227]
	v_mov_b32_e32 v138, v226
	v_mov_b32_e32 v139, v226
	v_pk_mul_f32 v[134:135], v[134:135], v[138:139]
	v_pk_mul_f32 v[140:141], v[132:133], v[226:227]
	v_pk_mul_f32 v[138:139], v[130:131], v[138:139]
	s_cbranch_vccnz .LBB0_199
	ds_swizzle_b32 v130, v140 offset:swizzle(SWAP,16)
	ds_swizzle_b32 v128, v142 offset:swizzle(SWAP,16)
	ds_swizzle_b32 v131, v141 offset:swizzle(SWAP,16)
	ds_swizzle_b32 v129, v143 offset:swizzle(SWAP,16)
	ds_swizzle_b32 v224, v134 offset:swizzle(SWAP,16)
	ds_swizzle_b32 v220, v138 offset:swizzle(SWAP,16)
	ds_swizzle_b32 v225, v135 offset:swizzle(SWAP,16)
	ds_swizzle_b32 v221, v139 offset:swizzle(SWAP,16)
	s_and_saveexec_b64 s[0:1], s[46:47]
	s_xor_b64 s[0:1], exec, s[0:1]
	s_cbranch_execz .LBB0_196
	s_and_saveexec_b64 s[4:5], s[44:45]
	s_cbranch_execz .LBB0_195
	s_waitcnt lgkmcnt(0)
	v_pk_mul_f32 v[130:131], v[164:165], v[130:131]
	v_pk_mul_f32 v[132:133], v[166:167], v[224:225]
	v_pk_fma_f32 v[140:141], v[140:141], v[160:161], v[130:131]
	v_pk_mul_f32 v[130:131], v[150:151], v[220:221]
	v_pk_mul_f32 v[128:129], v[148:149], v[128:129]
	v_pk_fma_f32 v[134:135], v[134:135], v[162:163], v[132:133]
	v_pk_fma_f32 v[138:139], v[138:139], v[146:147], v[130:131]
	v_pk_fma_f32 v[142:143], v[142:143], v[144:145], v[128:129]

.LBB0_201:
	s_waitcnt lgkmcnt(0)
	v_cvt_pk_bf16_f32 v128, v140, v141
	v_cvt_pk_bf16_f32 v129, v134, v135
	v_cvt_pk_bf16_f32 v130, v142, v143
	v_cvt_pk_bf16_f32 v131, v138, v139
	global_store_dwordx4 v[136:137], v[128:131], off offset:256 sc0 sc1
	v_pk_mul_f32 v[94:95], v[94:95], v[222:223] op_sel_hi:[1,0]
	s_and_b64 vcc, exec, s[42:43]
	v_pk_mul_f32 v[130:131], v[92:93], v[222:223] op_sel_hi:[1,0]
	v_pk_mul_f32 v[128:129], v[90:91], v[222:223] op_sel_hi:[1,0]
	v_pk_mul_f32 v[132:133], v[88:89], v[222:223] op_sel_hi:[1,0]
	s_cbranch_vccnz .LBB0_209
	ds_swizzle_b32 v90, v130 offset:swizzle(SWAP,16)
	ds_swizzle_b32 v88, v132 offset:swizzle(SWAP,16)
	ds_swizzle_b32 v91, v131 offset:swizzle(SWAP,16)
	ds_swizzle_b32 v89, v133 offset:swizzle(SWAP,16)
	ds_swizzle_b32 v136, v94 offset:swizzle(SWAP,16)
	ds_swizzle_b32 v134, v128 offset:swizzle(SWAP,16)
	ds_swizzle_b32 v137, v95 offset:swizzle(SWAP,16)
	ds_swizzle_b32 v135, v129 offset:swizzle(SWAP,16)
	s_and_saveexec_b64 s[0:1], s[46:47]
	s_xor_b64 s[0:1], exec, s[0:1]
	s_cbranch_execz .LBB0_206
	s_and_saveexec_b64 s[4:5], s[44:45]
	s_cbranch_execz .LBB0_205
	s_waitcnt lgkmcnt(0)
	v_pk_mul_f32 v[90:91], v[116:117], v[90:91]
	v_pk_mul_f32 v[92:93], v[118:119], v[136:137]
	v_pk_fma_f32 v[130:131], v[130:131], v[108:109], v[90:91]
	v_pk_mul_f32 v[90:91], v[102:103], v[134:135]
	v_pk_mul_f32 v[88:89], v[100:101], v[88:89]
	v_pk_fma_f32 v[94:95], v[94:95], v[110:111], v[92:93]
	v_pk_fma_f32 v[128:129], v[128:129], v[98:99], v[90:91]
	v_pk_fma_f32 v[132:133], v[132:133], v[96:97], v[88:89]

.LBB0_211:
	s_waitcnt lgkmcnt(0)
	v_mov_b64_e32 v[88:89], s[52:53]
	v_mad_i64_i32 v[88:89], s[0:1], v216, s15, v[88:89]
	v_cvt_pk_bf16_f32 v90, v130, v131
	v_cvt_pk_bf16_f32 v91, v94, v95
	v_lshl_add_u64 v[88:89], v[204:205], 1, v[88:89]
	v_mov_b32_e32 v223, v222
	v_cvt_pk_bf16_f32 v92, v132, v133
	v_cvt_pk_bf16_f32 v93, v128, v129
	global_store_dwordx4 v[88:89], v[90:93], off sc0 sc1
	s_and_b64 vcc, exec, s[42:43]
	v_pk_mul_f32 v[94:95], v[80:81], v[222:223]
	v_mov_b32_e32 v90, v222
	v_mov_b32_e32 v91, v222
	v_pk_mul_f32 v[86:87], v[86:87], v[90:91]
	v_pk_mul_f32 v[92:93], v[84:85], v[222:223]
	v_pk_mul_f32 v[90:91], v[82:83], v[90:91]
	s_cbranch_vccnz .LBB0_219
	ds_swizzle_b32 v82, v92 offset:swizzle(SWAP,16)
	ds_swizzle_b32 v80, v94 offset:swizzle(SWAP,16)
	ds_swizzle_b32 v83, v93 offset:swizzle(SWAP,16)
	ds_swizzle_b32 v81, v95 offset:swizzle(SWAP,16)
	ds_swizzle_b32 v130, v86 offset:swizzle(SWAP,16)
	ds_swizzle_b32 v128, v90 offset:swizzle(SWAP,16)
	ds_swizzle_b32 v131, v87 offset:swizzle(SWAP,16)
	ds_swizzle_b32 v129, v91 offset:swizzle(SWAP,16)
	s_and_saveexec_b64 s[0:1], s[46:47]
	s_xor_b64 s[0:1], exec, s[0:1]
	s_cbranch_execz .LBB0_216
	s_and_saveexec_b64 s[4:5], s[44:45]
	s_cbranch_execz .LBB0_215
	s_waitcnt lgkmcnt(0)
	v_pk_mul_f32 v[82:83], v[116:117], v[82:83]
	v_pk_mul_f32 v[84:85], v[118:119], v[130:131]
	v_pk_fma_f32 v[92:93], v[92:93], v[108:109], v[82:83]
	v_pk_mul_f32 v[82:83], v[102:103], v[128:129]
	v_pk_mul_f32 v[80:81], v[100:101], v[80:81]
	v_pk_fma_f32 v[86:87], v[86:87], v[110:111], v[84:85]
	v_pk_fma_f32 v[90:91], v[90:91], v[98:99], v[82:83]
	v_pk_fma_f32 v[94:95], v[94:95], v[96:97], v[80:81]

.LBB0_221:
	s_waitcnt lgkmcnt(0)
	v_cvt_pk_bf16_f32 v80, v92, v93
	v_cvt_pk_bf16_f32 v81, v86, v87
	v_cvt_pk_bf16_f32 v82, v94, v95
	v_cvt_pk_bf16_f32 v83, v90, v91
	global_store_dwordx4 v[88:89], v[80:83], off offset:256 sc0 sc1
	s_and_b64 vcc, exec, s[42:43]
	s_nop 0
	v_add_u32_e32 v80, 0x80, v206
	v_ashrrev_i32_e32 v81, 31, v80
	s_cbranch_vccnz .LBB0_223
	v_lshlrev_b64 v[82:83], 6, v[80:81]
	v_lshl_add_u64 v[82:83], s[56:57], 0, v[82:83]
	v_lshlrev_b64 v[82:83], 6, v[206:207]
	v_lshl_add_u64 v[82:83], s[56:57], 0, v[82:83]
	s_mov_b64 s[0:1], 0x2400
	v_lshl_add_u64 v[84:85], v[82:83], 0, s[0:1]
	v_add_co_u32_e32 v82, vcc, s11, v82
	s_nop 1
	v_addc_co_u32_e32 v83, vcc, 0, v83, vcc
	v_and_b32_e32 v120, 0xff, v206
	v_lshlrev_b32_e32 v120, 6, v120
	v_add_u32_e32 v120, 0x24000, v120
	ds_read_b128 v[156:159], v120 offset:8240
	ds_read_b128 v[172:175], v120 offset:8224
	ds_read_b128 v[152:155], v120 offset:8208
	ds_read_b128 v[168:171], v120 offset:8192
	ds_read_b128 v[112:115], v120 offset:9264
	ds_read_b128 v[124:127], v120 offset:9248
	ds_read_b128 v[104:107], v120 offset:9232
	ds_read_b128 v[120:123], v120 offset:9216

.LBB0_233:
	s_waitcnt lgkmcnt(0)
	v_mov_b64_e32 v[72:73], s[52:53]
	v_mad_i64_i32 v[72:73], s[0:1], v80, s15, v[72:73]
	v_cvt_pk_bf16_f32 v74, v84, v85
	v_cvt_pk_bf16_f32 v75, v78, v79
	v_lshl_add_u64 v[72:73], v[204:205], 1, v[72:73]
	v_mov_b32_e32 v219, v218
	v_cvt_pk_bf16_f32 v76, v86, v87
	v_cvt_pk_bf16_f32 v77, v82, v83
	global_store_dwordx4 v[72:73], v[74:77], off sc0 sc1
	s_and_b64 vcc, exec, s[42:43]
	v_pk_mul_f32 v[78:79], v[64:65], v[218:219]
	v_mov_b32_e32 v74, v218
	v_mov_b32_e32 v75, v218
	v_pk_mul_f32 v[70:71], v[70:71], v[74:75]
	v_pk_mul_f32 v[76:77], v[68:69], v[218:219]
	v_pk_mul_f32 v[74:75], v[66:67], v[74:75]
	s_cbranch_vccnz .LBB0_241
	ds_swizzle_b32 v66, v76 offset:swizzle(SWAP,16)
	ds_swizzle_b32 v64, v78 offset:swizzle(SWAP,16)
	ds_swizzle_b32 v67, v77 offset:swizzle(SWAP,16)
	ds_swizzle_b32 v65, v79 offset:swizzle(SWAP,16)
	ds_swizzle_b32 v82, v70 offset:swizzle(SWAP,16)
	ds_swizzle_b32 v80, v74 offset:swizzle(SWAP,16)
	ds_swizzle_b32 v83, v71 offset:swizzle(SWAP,16)
	ds_swizzle_b32 v81, v75 offset:swizzle(SWAP,16)
	s_and_saveexec_b64 s[0:1], s[46:47]
	s_xor_b64 s[0:1], exec, s[0:1]
	s_cbranch_execz .LBB0_238
	s_and_saveexec_b64 s[4:5], s[44:45]
	s_cbranch_execz .LBB0_237
	s_waitcnt lgkmcnt(0)
	v_pk_mul_f32 v[66:67], v[172:173], v[66:67]
	v_pk_mul_f32 v[68:69], v[174:175], v[82:83]
	v_pk_fma_f32 v[76:77], v[76:77], v[168:169], v[66:67]
	v_pk_mul_f32 v[66:67], v[158:159], v[80:81]
	v_pk_mul_f32 v[64:65], v[156:157], v[64:65]
	v_pk_fma_f32 v[70:71], v[70:71], v[170:171], v[68:69]
	v_pk_fma_f32 v[74:75], v[74:75], v[154:155], v[66:67]
	v_pk_fma_f32 v[78:79], v[78:79], v[152:153], v[64:65]

.LBB0_243:
	s_waitcnt lgkmcnt(0)
	v_cvt_pk_bf16_f32 v64, v76, v77
	v_cvt_pk_bf16_f32 v65, v70, v71
	v_cvt_pk_bf16_f32 v66, v78, v79
	v_cvt_pk_bf16_f32 v67, v74, v75
	global_store_dwordx4 v[72:73], v[64:67], off offset:256 sc0 sc1
	v_pk_mul_f32 v[54:55], v[54:55], v[214:215] op_sel_hi:[1,0]
	s_and_b64 vcc, exec, s[42:43]
	v_pk_mul_f32 v[66:67], v[52:53], v[214:215] op_sel_hi:[1,0]
	v_pk_mul_f32 v[64:65], v[50:51], v[214:215] op_sel_hi:[1,0]
	v_pk_mul_f32 v[68:69], v[48:49], v[214:215] op_sel_hi:[1,0]
	s_cbranch_vccnz .LBB0_251
	ds_swizzle_b32 v50, v66 offset:swizzle(SWAP,16)
	ds_swizzle_b32 v48, v68 offset:swizzle(SWAP,16)
	ds_swizzle_b32 v51, v67 offset:swizzle(SWAP,16)
	ds_swizzle_b32 v49, v69 offset:swizzle(SWAP,16)
	ds_swizzle_b32 v72, v54 offset:swizzle(SWAP,16)
	ds_swizzle_b32 v70, v64 offset:swizzle(SWAP,16)
	ds_swizzle_b32 v73, v55 offset:swizzle(SWAP,16)
	ds_swizzle_b32 v71, v65 offset:swizzle(SWAP,16)
	s_and_saveexec_b64 s[0:1], s[46:47]
	s_xor_b64 s[0:1], exec, s[0:1]
	s_cbranch_execz .LBB0_248
	s_and_saveexec_b64 s[4:5], s[44:45]
	s_cbranch_execz .LBB0_247
	s_waitcnt lgkmcnt(0)
	v_pk_mul_f32 v[50:51], v[124:125], v[50:51]
	v_pk_mul_f32 v[52:53], v[126:127], v[72:73]
	v_pk_fma_f32 v[66:67], v[66:67], v[120:121], v[50:51]
	v_pk_mul_f32 v[50:51], v[114:115], v[70:71]
	v_pk_mul_f32 v[48:49], v[112:113], v[48:49]
	v_pk_fma_f32 v[54:55], v[54:55], v[122:123], v[52:53]
	v_pk_fma_f32 v[64:65], v[64:65], v[106:107], v[50:51]
	v_pk_fma_f32 v[68:69], v[68:69], v[104:105], v[48:49]

.LBB0_253:
	s_waitcnt lgkmcnt(0)
	v_mov_b64_e32 v[48:49], s[52:53]
	v_mad_i64_i32 v[48:49], s[0:1], v210, s15, v[48:49]
	v_cvt_pk_bf16_f32 v50, v66, v67
	v_cvt_pk_bf16_f32 v51, v54, v55
	v_lshl_add_u64 v[48:49], v[204:205], 1, v[48:49]
	v_mov_b32_e32 v215, v214
	v_cvt_pk_bf16_f32 v52, v68, v69
	v_cvt_pk_bf16_f32 v53, v64, v65
	global_store_dwordx4 v[48:49], v[50:53], off sc0 sc1
	s_and_b64 vcc, exec, s[42:43]
	v_pk_mul_f32 v[54:55], v[32:33], v[214:215]
	v_mov_b32_e32 v50, v214
	v_mov_b32_e32 v51, v214
	v_pk_mul_f32 v[38:39], v[38:39], v[50:51]
	v_pk_mul_f32 v[52:53], v[36:37], v[214:215]
	v_pk_mul_f32 v[50:51], v[34:35], v[50:51]
	s_cbranch_vccnz .LBB0_261
	ds_swizzle_b32 v34, v52 offset:swizzle(SWAP,16)
	ds_swizzle_b32 v32, v54 offset:swizzle(SWAP,16)
	ds_swizzle_b32 v35, v53 offset:swizzle(SWAP,16)
	ds_swizzle_b32 v33, v55 offset:swizzle(SWAP,16)
	ds_swizzle_b32 v66, v38 offset:swizzle(SWAP,16)
	ds_swizzle_b32 v64, v50 offset:swizzle(SWAP,16)
	ds_swizzle_b32 v67, v39 offset:swizzle(SWAP,16)
	ds_swizzle_b32 v65, v51 offset:swizzle(SWAP,16)
	s_and_saveexec_b64 s[0:1], s[46:47]
	s_xor_b64 s[0:1], exec, s[0:1]
	s_cbranch_execz .LBB0_258
	s_and_saveexec_b64 s[4:5], s[44:45]
	s_cbranch_execz .LBB0_257
	s_waitcnt lgkmcnt(0)
	v_pk_mul_f32 v[34:35], v[124:125], v[34:35]
	v_pk_mul_f32 v[36:37], v[126:127], v[66:67]
	v_pk_fma_f32 v[52:53], v[52:53], v[120:121], v[34:35]
	v_pk_mul_f32 v[34:35], v[114:115], v[64:65]
	v_pk_mul_f32 v[32:33], v[112:113], v[32:33]
	v_pk_fma_f32 v[38:39], v[38:39], v[122:123], v[36:37]
	v_pk_fma_f32 v[50:51], v[50:51], v[106:107], v[34:35]
	v_pk_fma_f32 v[54:55], v[54:55], v[104:105], v[32:33]

.LBB0_263:
	s_and_b64 vcc, exec, s[42:43]
	s_waitcnt lgkmcnt(0)
	v_cvt_pk_bf16_f32 v32, v52, v53
	v_cvt_pk_bf16_f32 v33, v38, v39
	v_cvt_pk_bf16_f32 v34, v54, v55
	v_cvt_pk_bf16_f32 v35, v50, v51
	global_store_dwordx4 v[48:49], v[32:35], off offset:256 sc0 sc1
	s_cbranch_vccnz .LBB0_265
	s_nop 0
	v_lshlrev_b64 v[32:33], 6, v[202:203]
	v_lshl_add_u64 v[32:33], s[56:57], 0, v[32:33]
	v_lshlrev_b64 v[32:33], 6, v[206:207]
	v_lshl_add_u64 v[32:33], s[56:57], 0, v[32:33]
	v_lshl_add_u64 v[34:35], v[32:33], 0, s[76:77]
	v_add_co_u32_e32 v32, vcc, s11, v32
	s_nop 1
	v_addc_co_u32_e32 v33, vcc, 0, v33, vcc
	v_and_b32_e32 v108, 0xff, v206
	v_lshlrev_b32_e32 v108, 6, v108
	v_add_u32_e32 v108, 0x24000, v108
	ds_read_b128 v[148:151], v108 offset:10288
	ds_read_b128 v[164:167], v108 offset:10272
	ds_read_b128 v[144:147], v108 offset:10256
	ds_read_b128 v[160:163], v108 offset:10240
	ds_read_b128 v[100:103], v108 offset:11312
	ds_read_b128 v[116:119], v108 offset:11296
	ds_read_b128 v[96:99], v108 offset:11280
	ds_read_b128 v[108:111], v108 offset:11264

.LBB0_275:
	s_waitcnt lgkmcnt(0)
	v_mov_b64_e32 v[24:25], s[52:53]
	v_mad_i64_i32 v[24:25], s[0:1], v202, s15, v[24:25]
	v_cvt_pk_bf16_f32 v26, v34, v35
	v_cvt_pk_bf16_f32 v27, v30, v31
	v_lshl_add_u64 v[24:25], v[204:205], 1, v[24:25]
	v_mov_b32_e32 v213, v212
	v_cvt_pk_bf16_f32 v28, v36, v37
	v_cvt_pk_bf16_f32 v29, v32, v33
	global_store_dwordx4 v[24:25], v[26:29], off sc0 sc1
	s_and_b64 vcc, exec, s[42:43]
	v_pk_mul_f32 v[30:31], v[16:17], v[212:213]
	v_mov_b32_e32 v26, v212
	v_mov_b32_e32 v27, v212
	v_pk_mul_f32 v[22:23], v[22:23], v[26:27]
	v_pk_mul_f32 v[28:29], v[20:21], v[212:213]
	v_pk_mul_f32 v[26:27], v[18:19], v[26:27]
	s_cbranch_vccnz .LBB0_283
	ds_swizzle_b32 v18, v28 offset:swizzle(SWAP,16)
	ds_swizzle_b32 v16, v30 offset:swizzle(SWAP,16)
	ds_swizzle_b32 v19, v29 offset:swizzle(SWAP,16)
	ds_swizzle_b32 v17, v31 offset:swizzle(SWAP,16)
	ds_swizzle_b32 v34, v22 offset:swizzle(SWAP,16)
	ds_swizzle_b32 v32, v26 offset:swizzle(SWAP,16)
	ds_swizzle_b32 v35, v23 offset:swizzle(SWAP,16)
	ds_swizzle_b32 v33, v27 offset:swizzle(SWAP,16)
	s_and_saveexec_b64 s[0:1], s[46:47]
	s_xor_b64 s[0:1], exec, s[0:1]
	s_cbranch_execz .LBB0_280
	s_and_saveexec_b64 s[4:5], s[44:45]
	s_cbranch_execz .LBB0_279
	s_waitcnt lgkmcnt(0)
	v_pk_mul_f32 v[18:19], v[164:165], v[18:19]
	v_pk_mul_f32 v[20:21], v[166:167], v[34:35]
	v_pk_fma_f32 v[28:29], v[28:29], v[160:161], v[18:19]
	v_pk_mul_f32 v[18:19], v[150:151], v[32:33]
	v_pk_mul_f32 v[16:17], v[148:149], v[16:17]
	v_pk_fma_f32 v[22:23], v[22:23], v[162:163], v[20:21]
	v_pk_fma_f32 v[26:27], v[26:27], v[146:147], v[18:19]
	v_pk_fma_f32 v[30:31], v[30:31], v[144:145], v[16:17]

.LBB0_285:
	s_waitcnt lgkmcnt(0)
	v_cvt_pk_bf16_f32 v16, v28, v29
	v_cvt_pk_bf16_f32 v17, v22, v23
	v_cvt_pk_bf16_f32 v18, v30, v31
	v_cvt_pk_bf16_f32 v19, v26, v27
	global_store_dwordx4 v[24:25], v[16:19], off offset:256 sc0 sc1
	v_pk_mul_f32 v[14:15], v[14:15], v[208:209] op_sel_hi:[1,0]
	s_and_b64 vcc, exec, s[42:43]
	v_pk_mul_f32 v[18:19], v[12:13], v[208:209] op_sel_hi:[1,0]
	v_pk_mul_f32 v[16:17], v[10:11], v[208:209] op_sel_hi:[1,0]
	v_pk_mul_f32 v[20:21], v[8:9], v[208:209] op_sel_hi:[1,0]
	s_cbranch_vccnz .LBB0_293
	ds_swizzle_b32 v10, v18 offset:swizzle(SWAP,16)
	ds_swizzle_b32 v8, v20 offset:swizzle(SWAP,16)
	ds_swizzle_b32 v11, v19 offset:swizzle(SWAP,16)
	ds_swizzle_b32 v9, v21 offset:swizzle(SWAP,16)
	ds_swizzle_b32 v24, v14 offset:swizzle(SWAP,16)
	ds_swizzle_b32 v22, v16 offset:swizzle(SWAP,16)
	ds_swizzle_b32 v25, v15 offset:swizzle(SWAP,16)
	ds_swizzle_b32 v23, v17 offset:swizzle(SWAP,16)
	s_and_saveexec_b64 s[0:1], s[46:47]
	s_xor_b64 s[0:1], exec, s[0:1]
	s_cbranch_execz .LBB0_290
	s_and_saveexec_b64 s[4:5], s[44:45]
	s_cbranch_execz .LBB0_289
	s_waitcnt lgkmcnt(0)
	v_pk_mul_f32 v[10:11], v[116:117], v[10:11]
	v_pk_mul_f32 v[12:13], v[118:119], v[24:25]
	v_pk_fma_f32 v[18:19], v[18:19], v[108:109], v[10:11]
	v_pk_mul_f32 v[10:11], v[102:103], v[22:23]
	v_pk_mul_f32 v[8:9], v[100:101], v[8:9]
	v_pk_fma_f32 v[14:15], v[14:15], v[110:111], v[12:13]
	v_pk_fma_f32 v[16:17], v[16:17], v[98:99], v[10:11]
	v_pk_fma_f32 v[20:21], v[20:21], v[96:97], v[8:9]

.LBB0_295:
	s_waitcnt lgkmcnt(0)
	v_mov_b64_e32 v[8:9], s[52:53]
	v_mad_i64_i32 v[8:9], s[0:1], v200, s15, v[8:9]
	v_cvt_pk_bf16_f32 v10, v18, v19
	v_cvt_pk_bf16_f32 v11, v14, v15
	v_lshl_add_u64 v[8:9], v[204:205], 1, v[8:9]
	v_mov_b32_e32 v209, v208
	v_cvt_pk_bf16_f32 v12, v20, v21
	v_cvt_pk_bf16_f32 v13, v16, v17
	global_store_dwordx4 v[8:9], v[10:13], off sc0 sc1
	s_and_b64 vcc, exec, s[42:43]
	v_pk_mul_f32 v[14:15], v[0:1], v[208:209]
	v_mov_b32_e32 v10, v208
	v_mov_b32_e32 v11, v208
	v_pk_mul_f32 v[6:7], v[6:7], v[10:11]
	v_pk_mul_f32 v[12:13], v[4:5], v[208:209]
	v_pk_mul_f32 v[10:11], v[2:3], v[10:11]
	s_cbranch_vccnz .LBB0_303
	ds_swizzle_b32 v2, v12 offset:swizzle(SWAP,16)
	ds_swizzle_b32 v0, v14 offset:swizzle(SWAP,16)
	ds_swizzle_b32 v3, v13 offset:swizzle(SWAP,16)
	ds_swizzle_b32 v1, v15 offset:swizzle(SWAP,16)
	ds_swizzle_b32 v18, v6 offset:swizzle(SWAP,16)
	ds_swizzle_b32 v16, v10 offset:swizzle(SWAP,16)
	ds_swizzle_b32 v19, v7 offset:swizzle(SWAP,16)
	ds_swizzle_b32 v17, v11 offset:swizzle(SWAP,16)
	s_and_saveexec_b64 s[0:1], s[46:47]
	s_xor_b64 s[0:1], exec, s[0:1]
	s_cbranch_execz .LBB0_300
	s_and_saveexec_b64 s[4:5], s[44:45]
	s_cbranch_execz .LBB0_299
	s_waitcnt lgkmcnt(0)
	v_pk_mul_f32 v[2:3], v[116:117], v[2:3]
	v_pk_mul_f32 v[4:5], v[118:119], v[18:19]
	v_pk_fma_f32 v[12:13], v[12:13], v[108:109], v[2:3]
	v_pk_mul_f32 v[2:3], v[102:103], v[16:17]
	v_pk_mul_f32 v[0:1], v[100:101], v[0:1]
	v_pk_fma_f32 v[6:7], v[6:7], v[110:111], v[4:5]
	v_pk_fma_f32 v[10:11], v[10:11], v[98:99], v[2:3]
	v_pk_fma_f32 v[14:15], v[14:15], v[96:97], v[0:1]

.LBB0_305:
	s_andn2_b64 vcc, exec, s[38:39]
	s_mov_b64 s[0:1], -1
	s_waitcnt lgkmcnt(0)
	v_cvt_pk_bf16_f32 v0, v12, v13
	v_cvt_pk_bf16_f32 v1, v6, v7
	v_cvt_pk_bf16_f32 v2, v14, v15
	v_cvt_pk_bf16_f32 v3, v10, v11
	global_store_dwordx4 v[8:9], v[0:3], off offset:256 sc0 sc1
	s_cbranch_vccnz .LBB0_104
	s_andn2_b64 vcc, exec, s[48:49]
	s_cbranch_vccnz .LBB0_103
	s_barrier
	s_branch .LBB0_103

.LBB0_775:
	s_or_saveexec_b64 s[44:45], s[0:1]
	s_lshl_b32 s0, s46, 2
	s_add_i32 s4, s0, s61
	s_ashr_i32 s5, s4, 31
	s_lshl_b64 s[0:1], s[4:5], 2
	s_xor_b64 exec, exec, s[44:45]
	s_cbranch_execz .LBB0_777
	v_or_b32_e32 v179, s0, v176
	v_cvt_pk_bf16_f32 v144, v216, v217
	v_cvt_pk_bf16_f32 v145, v218, v219
	v_cvt_pk_bf16_f32 v146, v152, v153
	v_mov_b64_e32 v[152:153], s[54:55]
	v_cvt_pk_bf16_f32 v147, v156, v157
	v_mad_u64_u32 v[152:153], s[6:7], v179, s25, v[152:153]
	v_mov_b32_e32 v156, 0x1600
	v_mad_i32_i24 v153, s1, v156, v153
	v_lshl_add_u64 v[152:153], v[192:193], 1, v[152:153]
	v_lshl_or_b32 v178, s4, 1, v176
	global_store_dwordx4 v[152:153], v[144:147], off sc0 sc1
	s_nop 1
	v_cvt_pk_bf16_f32 v144, v154, v155
	v_cvt_pk_bf16_f32 v145, v158, v159
	v_cvt_pk_bf16_f32 v146, v150, v151
	v_cvt_pk_bf16_f32 v147, v148, v149
	v_mov_b64_e32 v[148:149], s[56:57]
	v_mad_u64_u32 v[220:221], s[6:7], v178, s25, v[148:149]
	v_mad_i32_i24 v221, s5, v156, v221
.LBB0_777:
	s_or_b64 exec, exec, s[44:45]
	v_lshlrev_b64 v[150:151], 1, v[192:193]
	v_lshl_add_u64 v[152:153], v[220:221], 0, v[150:151]
	s_waitcnt lgkmcnt(0)
	v_pk_mul_f32 v[108:109], v[108:109], v[214:215] op_sel_hi:[1,0]
	global_store_dwordx4 v[152:153], v[144:147], off sc0 sc1
	ds_bpermute_b32 v144, v173, v108
	ds_bpermute_b32 v145, v175, v108
	v_cmp_eq_u32_e64 s[46:47], 0, v176
	s_waitcnt vmcnt(2)
	v_fma_f32 v108, v140, v108, v128
	ds_bpermute_b32 v146, v173, v109
	s_waitcnt lgkmcnt(2)
	v_cndmask_b32_e64 v158, v144, v225, s[46:47]
	s_waitcnt lgkmcnt(1)
	v_cndmask_b32_e32 v159, v145, v224, vcc
	v_fmac_f32_e32 v108, v136, v158
	ds_bpermute_b32 v147, v175, v109
	v_fmac_f32_e32 v108, v132, v159
	v_mul_f32_e32 v158, 0xbfb8aa3b, v108
	v_exp_f32_e32 v158, v158
	v_pk_mul_f32 v[110:111], v[110:111], v[214:215] op_sel_hi:[1,0]
	ds_bpermute_b32 v153, v173, v110
	s_waitcnt lgkmcnt(2)
	v_cndmask_b32_e64 v159, v146, v222, s[46:47]
	v_fma_f32 v109, v141, v109, v129
	ds_bpermute_b32 v152, v173, v111
	ds_bpermute_b32 v154, v175, v110
	s_waitcnt lgkmcnt(3)
	v_cndmask_b32_e32 v179, v147, v215, vcc
	v_fmac_f32_e32 v109, v137, v159
	ds_bpermute_b32 v155, v175, v111
	v_add_f32_e32 v158, 1.0, v158
	v_fmac_f32_e32 v109, v133, v179
	v_rcp_f32_e32 v158, v158
	v_mul_f32_e32 v159, 0xbfb8aa3b, v109
	v_exp_f32_e32 v159, v159
	s_waitcnt lgkmcnt(3)
	v_cndmask_b32_e64 v157, v153, v226, s[46:47]
	v_fma_f32 v110, v142, v110, v130
	s_waitcnt lgkmcnt(2)
	v_cndmask_b32_e64 v156, v152, v227, s[46:47]
	s_waitcnt lgkmcnt(1)
	v_cndmask_b32_e32 v179, v154, v213, vcc
	v_fmac_f32_e32 v110, v138, v157
	v_fma_f32 v111, v143, v111, v131
	v_pk_mul_f32 v[104:105], v[104:105], v[214:215] op_sel_hi:[1,0]
	s_waitcnt lgkmcnt(0)
	v_cndmask_b32_e32 v178, v155, v223, vcc
	v_mul_f32_e32 v108, v108, v158
	v_fmac_f32_e32 v110, v134, v179
	v_fmac_f32_e32 v111, v139, v156
	v_mul_f32_e32 v104, v104, v108
	v_add_f32_e32 v108, 1.0, v159
	v_mul_f32_e32 v157, 0xbfb8aa3b, v110
	v_fmac_f32_e32 v111, v135, v178
	v_rcp_f32_e32 v108, v108
	v_exp_f32_e32 v157, v157
	v_mul_f32_e32 v156, 0xbfb8aa3b, v111
	v_exp_f32_e32 v156, v156
	v_pk_mul_f32 v[102:103], v[102:103], v[214:215] op_sel_hi:[1,0]
	v_mul_f32_e32 v108, v109, v108
	v_add_f32_e32 v109, 1.0, v157
	ds_bpermute_b32 v157, v173, v103
	v_rcp_f32_e32 v109, v109
	v_add_f32_e32 v156, 1.0, v156
	ds_bpermute_b32 v158, v175, v103
	v_rcp_f32_e32 v156, v156
	v_pk_mul_f32 v[106:107], v[106:107], v[214:215] op_sel_hi:[1,0]
	v_mul_f32_e32 v105, v105, v108
	v_mul_f32_e32 v108, v110, v109
	s_waitcnt lgkmcnt(1)
	v_cndmask_b32_e64 v180, v157, v211, s[46:47]
	v_fma_f32 v103, v127, v103, v115
	v_mul_f32_e32 v106, v106, v108
	v_mul_f32_e32 v108, v111, v156
	ds_bpermute_b32 v156, v173, v102
	s_waitcnt lgkmcnt(1)
	v_cndmask_b32_e32 v181, v158, v209, vcc
	v_fmac_f32_e32 v103, v123, v180
	ds_bpermute_b32 v159, v175, v102
	v_fmac_f32_e32 v103, v119, v181
	v_mul_f32_e32 v180, 0xbfb8aa3b, v103
	v_exp_f32_e32 v180, v180
	v_pk_mul_f32 v[100:101], v[100:101], v[214:215] op_sel_hi:[1,0]
	ds_bpermute_b32 v110, v173, v101
	s_waitcnt lgkmcnt(2)
	v_cndmask_b32_e64 v181, v156, v197, s[46:47]
	v_fma_f32 v102, v126, v102, v114
	v_mul_f32_e32 v107, v107, v108
	ds_bpermute_b32 v108, v173, v100
	ds_bpermute_b32 v111, v175, v101
	s_waitcnt lgkmcnt(3)
	v_cndmask_b32_e32 v182, v159, v201, vcc
	v_fmac_f32_e32 v102, v122, v181
	ds_bpermute_b32 v109, v175, v100
	v_add_f32_e32 v180, 1.0, v180
	v_fmac_f32_e32 v102, v118, v182
	v_rcp_f32_e32 v180, v180
	v_mul_f32_e32 v181, 0xbfb8aa3b, v102
	v_exp_f32_e32 v181, v181
	s_waitcnt lgkmcnt(3)
	v_cndmask_b32_e64 v179, v110, v205, s[46:47]
	v_fma_f32 v101, v125, v101, v113
	s_waitcnt lgkmcnt(2)
	v_cndmask_b32_e64 v178, v108, v203, s[46:47]
	s_waitcnt lgkmcnt(1)
	v_cndmask_b32_e32 v182, v111, v191, vcc
	v_fmac_f32_e32 v101, v121, v179
	v_fma_f32 v100, v124, v100, v112
	v_pk_mul_f32 v[98:99], v[98:99], v[214:215] op_sel_hi:[1,0]
	s_waitcnt lgkmcnt(0)
	v_cndmask_b32_e32 v183, v109, v195, vcc
	v_mul_f32_e32 v103, v103, v180
	v_fmac_f32_e32 v101, v117, v182
	v_fmac_f32_e32 v100, v120, v178
	v_mul_f32_e32 v103, v99, v103
	v_add_f32_e32 v99, 1.0, v181
	v_mul_f32_e32 v179, 0xbfb8aa3b, v101
	v_fmac_f32_e32 v100, v116, v183
	v_rcp_f32_e32 v99, v99
	v_exp_f32_e32 v179, v179
	v_mul_f32_e32 v178, 0xbfb8aa3b, v100
	v_exp_f32_e32 v178, v178
	v_mul_f32_e32 v99, v102, v99
	v_add_f32_e32 v102, 1.0, v179
	v_rcp_f32_e32 v102, v102
	v_add_f32_e32 v178, 1.0, v178
	v_rcp_f32_e32 v178, v178
	v_pk_mul_f32 v[96:97], v[96:97], v[214:215] op_sel_hi:[1,0]
	v_mul_f32_e32 v179, v98, v99
	v_mul_f32_e32 v98, v101, v102
	v_mul_f32_e32 v97, v97, v98
	v_mul_f32_e32 v98, v100, v178
	v_mul_f32_e32 v96, v96, v98
	v_cvt_pk_bf16_f32 v98, v104, v105
	v_cvt_pk_bf16_f32 v99, v106, v107
	v_cvt_pk_bf16_f32 v100, v96, v97
	v_mov_b64_e32 v[96:97], s[52:53]
	v_cvt_pk_bf16_f32 v101, v179, v103
	v_mad_i64_i32 v[102:103], s[6:7], v204, s25, v[96:97]
	v_lshl_add_u64 v[102:103], v[102:103], 0, v[150:151]
	v_pk_mul_f32 v[92:93], v[92:93], v[212:213] op_sel_hi:[1,0]
	global_store_dwordx4 v[102:103], v[98:101], off sc0 sc1
	ds_bpermute_b32 v98, v173, v92
	ds_bpermute_b32 v99, v175, v92
	v_fma_f32 v92, v140, v92, v128
	ds_bpermute_b32 v100, v173, v93
	ds_bpermute_b32 v103, v175, v93
	s_waitcnt lgkmcnt(3)
	v_cndmask_b32_e64 v144, v98, v144, s[46:47]
	s_waitcnt lgkmcnt(2)
	v_cndmask_b32_e32 v145, v99, v145, vcc
	v_fmac_f32_e32 v92, v136, v144
	v_fmac_f32_e32 v92, v132, v145
	v_mul_f32_e32 v144, 0xbfb8aa3b, v92
	v_exp_f32_e32 v144, v144
	v_pk_mul_f32 v[94:95], v[94:95], v[212:213] op_sel_hi:[1,0]
	ds_bpermute_b32 v102, v173, v94
	s_waitcnt lgkmcnt(2)
	v_cndmask_b32_e64 v145, v100, v146, s[46:47]
	v_fma_f32 v93, v141, v93, v129
	ds_bpermute_b32 v101, v173, v95
	ds_bpermute_b32 v104, v175, v94
	s_waitcnt lgkmcnt(3)
	v_cndmask_b32_e32 v147, v103, v147, vcc
	v_fmac_f32_e32 v93, v137, v145
	ds_bpermute_b32 v105, v175, v95
	v_add_f32_e32 v144, 1.0, v144
	v_fmac_f32_e32 v93, v133, v147
	v_rcp_f32_e32 v144, v144
	v_mul_f32_e32 v145, 0xbfb8aa3b, v93
	v_exp_f32_e32 v145, v145
	s_waitcnt lgkmcnt(3)
	v_cndmask_b32_e64 v107, v102, v153, s[46:47]
	v_fma_f32 v94, v142, v94, v130
	s_waitcnt lgkmcnt(2)
	v_cndmask_b32_e64 v106, v101, v152, s[46:47]
	s_waitcnt lgkmcnt(1)
	v_cndmask_b32_e32 v147, v104, v154, vcc
	v_fmac_f32_e32 v94, v138, v107
	v_fma_f32 v95, v143, v95, v131
	v_pk_mul_f32 v[88:89], v[88:89], v[212:213] op_sel_hi:[1,0]
	s_waitcnt lgkmcnt(0)
	v_cndmask_b32_e32 v146, v105, v155, vcc
	v_mul_f32_e32 v92, v92, v144
	v_fmac_f32_e32 v94, v134, v147
	v_fmac_f32_e32 v95, v139, v106
	v_mul_f32_e32 v88, v88, v92
	v_add_f32_e32 v92, 1.0, v145
	v_mul_f32_e32 v107, 0xbfb8aa3b, v94
	v_fmac_f32_e32 v95, v135, v146
	v_rcp_f32_e32 v92, v92
	v_exp_f32_e32 v107, v107
	v_mul_f32_e32 v106, 0xbfb8aa3b, v95
	v_exp_f32_e32 v106, v106
	v_pk_mul_f32 v[86:87], v[86:87], v[212:213] op_sel_hi:[1,0]
	v_mul_f32_e32 v92, v93, v92
	v_add_f32_e32 v93, 1.0, v107
	ds_bpermute_b32 v107, v173, v87
	v_rcp_f32_e32 v93, v93
	v_add_f32_e32 v106, 1.0, v106
	ds_bpermute_b32 v144, v175, v87
	v_rcp_f32_e32 v106, v106
	v_pk_mul_f32 v[90:91], v[90:91], v[212:213] op_sel_hi:[1,0]
	v_mul_f32_e32 v89, v89, v92
	v_mul_f32_e32 v92, v94, v93
	s_waitcnt lgkmcnt(1)
	v_cndmask_b32_e64 v146, v107, v157, s[46:47]
	v_fma_f32 v87, v127, v87, v115
	v_mul_f32_e32 v90, v90, v92
	v_mul_f32_e32 v92, v95, v106
	ds_bpermute_b32 v106, v173, v86
	s_waitcnt lgkmcnt(1)
	v_cndmask_b32_e32 v147, v144, v158, vcc
	v_fmac_f32_e32 v87, v123, v146
	ds_bpermute_b32 v145, v175, v86
	v_fmac_f32_e32 v87, v119, v147
	v_mul_f32_e32 v146, 0xbfb8aa3b, v87
	v_exp_f32_e32 v146, v146
	v_pk_mul_f32 v[84:85], v[84:85], v[212:213] op_sel_hi:[1,0]
	ds_bpermute_b32 v94, v173, v85
	s_waitcnt lgkmcnt(2)
	v_cndmask_b32_e64 v147, v106, v156, s[46:47]
	v_fma_f32 v86, v126, v86, v114
	v_mul_f32_e32 v91, v91, v92
	ds_bpermute_b32 v92, v173, v84
	ds_bpermute_b32 v95, v175, v85
	s_waitcnt lgkmcnt(3)
	v_cndmask_b32_e32 v152, v145, v159, vcc
	v_fmac_f32_e32 v86, v122, v147
	ds_bpermute_b32 v93, v175, v84
	v_add_f32_e32 v146, 1.0, v146
	v_fmac_f32_e32 v86, v118, v152
	v_rcp_f32_e32 v146, v146
	v_mul_f32_e32 v147, 0xbfb8aa3b, v86
	v_exp_f32_e32 v147, v147
	s_waitcnt lgkmcnt(3)
	v_cndmask_b32_e64 v110, v94, v110, s[46:47]
	v_fma_f32 v85, v125, v85, v113
	s_waitcnt lgkmcnt(2)
	v_cndmask_b32_e64 v108, v92, v108, s[46:47]
	s_waitcnt lgkmcnt(1)
	v_cndmask_b32_e32 v111, v95, v111, vcc
	v_fmac_f32_e32 v85, v121, v110
	v_fma_f32 v84, v124, v84, v112
	v_pk_mul_f32 v[82:83], v[82:83], v[212:213] op_sel_hi:[1,0]
	s_waitcnt lgkmcnt(0)
	v_cndmask_b32_e32 v109, v93, v109, vcc
	v_mul_f32_e32 v87, v87, v146
	v_fmac_f32_e32 v85, v117, v111
	v_fmac_f32_e32 v84, v120, v108
	v_mul_f32_e32 v83, v83, v87
	v_add_f32_e32 v87, 1.0, v147
	v_mul_f32_e32 v110, 0xbfb8aa3b, v85
	v_fmac_f32_e32 v84, v116, v109
	v_rcp_f32_e32 v87, v87
	v_exp_f32_e32 v110, v110
	v_mul_f32_e32 v108, 0xbfb8aa3b, v84
	v_exp_f32_e32 v108, v108
	v_mul_f32_e32 v86, v86, v87
	v_add_f32_e32 v87, 1.0, v110
	v_rcp_f32_e32 v87, v87
	v_add_f32_e32 v108, 1.0, v108
	v_rcp_f32_e32 v108, v108
	v_pk_mul_f32 v[80:81], v[80:81], v[212:213] op_sel_hi:[1,0]
	v_mul_f32_e32 v86, v82, v86
	v_mul_f32_e32 v82, v85, v87
	v_mul_f32_e32 v82, v81, v82
	v_mul_f32_e32 v81, v84, v108
	v_mul_f32_e32 v84, v80, v81
	v_cvt_pk_bf16_f32 v80, v88, v89
	v_cvt_pk_bf16_f32 v81, v90, v91
	v_cvt_pk_bf16_f32 v82, v84, v82
	v_mad_i64_i32 v[84:85], s[6:7], v200, s25, v[96:97]
	v_lshl_add_u64 v[84:85], v[84:85], 0, v[150:151]
	v_pk_mul_f32 v[76:77], v[76:77], v[210:211] op_sel_hi:[1,0]
	v_cvt_pk_bf16_f32 v83, v86, v83
	global_store_dwordx4 v[84:85], v[80:83], off sc0 sc1
	ds_bpermute_b32 v80, v173, v76
	ds_bpermute_b32 v81, v175, v76
	v_pk_mul_f32 v[78:79], v[78:79], v[210:211] op_sel_hi:[1,0]
	v_fma_f32 v88, v140, v76, v128
	ds_bpermute_b32 v82, v173, v77
	s_waitcnt lgkmcnt(2)
	v_cndmask_b32_e64 v80, v80, v98, s[46:47]
	ds_bpermute_b32 v87, v175, v79
	s_waitcnt lgkmcnt(2)
	v_cndmask_b32_e32 v81, v81, v99, vcc
	v_fmac_f32_e32 v88, v136, v80
	ds_bpermute_b32 v85, v175, v77
	v_fmac_f32_e32 v88, v132, v81
	v_mul_f32_e32 v80, 0xbfb8aa3b, v88
	v_exp_f32_e32 v80, v80
	s_waitcnt lgkmcnt(2)
	v_cndmask_b32_e64 v81, v82, v100, s[46:47]
	s_waitcnt lgkmcnt(1)
	v_cndmask_b32_e32 v82, v87, v105, vcc
	v_fma_f32 v87, v141, v77, v129
	s_waitcnt lgkmcnt(0)
	v_cndmask_b32_e32 v85, v85, v103, vcc
	v_fmac_f32_e32 v87, v137, v81
	v_add_f32_e32 v80, 1.0, v80
	v_fmac_f32_e32 v87, v133, v85
	ds_bpermute_b32 v84, v173, v78
	v_rcp_f32_e32 v80, v80
	v_mul_f32_e32 v81, 0xbfb8aa3b, v87
	ds_bpermute_b32 v86, v175, v78
	v_exp_f32_e32 v81, v81
	ds_bpermute_b32 v83, v173, v79
	v_pk_mul_f32 v[72:73], v[72:73], v[210:211] op_sel_hi:[1,0]
	v_mul_f32_e32 v80, v88, v80
	s_waitcnt lgkmcnt(2)
	v_cndmask_b32_e64 v84, v84, v102, s[46:47]
	v_mul_f32_e32 v72, v72, v80
	v_add_f32_e32 v80, 1.0, v81
	v_fma_f32 v81, v142, v78, v130
	s_waitcnt lgkmcnt(1)
	v_cndmask_b32_e32 v85, v86, v104, vcc
	v_fmac_f32_e32 v81, v138, v84
	s_waitcnt lgkmcnt(0)
	v_cndmask_b32_e64 v83, v83, v101, s[46:47]
	v_fmac_f32_e32 v81, v134, v85
	v_fma_f32 v85, v143, v79, v131
	v_fmac_f32_e32 v85, v139, v83
	v_mul_f32_e32 v84, 0xbfb8aa3b, v81
	v_fmac_f32_e32 v85, v135, v82
	v_exp_f32_e32 v84, v84
	v_mul_f32_e32 v82, 0xbfb8aa3b, v85
	v_exp_f32_e32 v82, v82
	v_rcp_f32_e32 v80, v80
	v_add_f32_e32 v83, 1.0, v84
	v_rcp_f32_e32 v83, v83
	v_add_f32_e32 v82, 1.0, v82
	v_rcp_f32_e32 v82, v82
	v_mul_f32_e32 v80, v87, v80
	v_pk_mul_f32 v[74:75], v[74:75], v[210:211] op_sel_hi:[1,0]
	v_mul_f32_e32 v73, v73, v80
	v_mul_f32_e32 v80, v81, v83
	v_pk_mul_f32 v[70:71], v[70:71], v[210:211] op_sel_hi:[1,0]
	v_mul_f32_e32 v74, v74, v80
	v_mul_f32_e32 v80, v85, v82
	ds_bpermute_b32 v85, v173, v71
	ds_bpermute_b32 v86, v175, v71
	v_fma_f32 v88, v127, v71, v115
	v_pk_mul_f32 v[68:69], v[68:69], v[210:211] op_sel_hi:[1,0]
	ds_bpermute_b32 v82, v173, v69
	s_waitcnt lgkmcnt(2)
	v_cndmask_b32_e64 v85, v85, v107, s[46:47]
	s_waitcnt lgkmcnt(1)
	v_cndmask_b32_e32 v86, v86, v144, vcc
	v_fmac_f32_e32 v88, v123, v85
	v_fmac_f32_e32 v88, v119, v86
	v_mul_f32_e32 v85, 0xbfb8aa3b, v88
	v_exp_f32_e32 v85, v85
	ds_bpermute_b32 v84, v173, v70
	ds_bpermute_b32 v87, v175, v70
	ds_bpermute_b32 v83, v175, v69
	v_add_f32_e32 v85, 1.0, v85
	v_rcp_f32_e32 v85, v85
	v_mul_f32_e32 v75, v75, v80
	ds_bpermute_b32 v80, v173, v68
	ds_bpermute_b32 v81, v175, v68
	v_pk_mul_f32 v[66:67], v[66:67], v[210:211] op_sel_hi:[1,0]
	v_mul_f32_e32 v85, v88, v85
	s_waitcnt lgkmcnt(5)
	v_cndmask_b32_e64 v82, v82, v94, s[46:47]
	s_waitcnt lgkmcnt(4)
	v_cndmask_b32_e64 v84, v84, v106, s[46:47]
	s_waitcnt lgkmcnt(3)
	v_cndmask_b32_e32 v86, v87, v145, vcc
	v_fma_f32 v87, v126, v70, v114
	v_mul_f32_e32 v67, v67, v85
	v_fma_f32 v85, v125, v69, v113
	v_fmac_f32_e32 v87, v122, v84
	s_waitcnt lgkmcnt(2)
	v_cndmask_b32_e32 v83, v83, v95, vcc
	v_fmac_f32_e32 v85, v121, v82
	s_waitcnt lgkmcnt(1)
	v_cndmask_b32_e64 v80, v80, v92, s[46:47]
	v_fmac_f32_e32 v87, v118, v86
	v_fmac_f32_e32 v85, v117, v83
	v_fma_f32 v83, v124, v68, v112
	s_waitcnt lgkmcnt(0)
	v_cndmask_b32_e32 v81, v81, v93, vcc
	v_mul_f32_e32 v84, 0xbfb8aa3b, v87
	v_fmac_f32_e32 v83, v120, v80
	v_exp_f32_e32 v84, v84
	v_mul_f32_e32 v82, 0xbfb8aa3b, v85
	v_fmac_f32_e32 v83, v116, v81
	v_exp_f32_e32 v82, v82
	v_mul_f32_e32 v80, 0xbfb8aa3b, v83
	v_exp_f32_e32 v80, v80
	v_add_f32_e32 v84, 1.0, v84
	v_rcp_f32_e32 v84, v84
	v_add_f32_e32 v82, 1.0, v82
	v_rcp_f32_e32 v82, v82
	v_add_f32_e32 v80, 1.0, v80
	v_rcp_f32_e32 v80, v80
	v_mul_f32_e32 v81, v87, v84
	v_pk_mul_f32 v[64:65], v[64:65], v[210:211] op_sel_hi:[1,0]
	v_mul_f32_e32 v81, v66, v81
	v_mul_f32_e32 v66, v85, v82
	v_mul_f32_e32 v66, v65, v66
	v_mul_f32_e32 v65, v83, v80
	v_mul_f32_e32 v80, v64, v65
	v_cvt_pk_bf16_f32 v64, v72, v73
	v_mad_i64_i32 v[72:73], s[6:7], v196, s25, v[96:97]
	v_cmp_lt_u32_e64 s[44:45], 13, v176
	v_lshl_add_u64 v[148:149], v[176:177], 0, -12
	v_lshl_add_u64 v[72:73], v[72:73], 0, v[150:151]
	v_cvt_pk_bf16_f32 v65, v74, v75
	v_cvt_pk_bf16_f32 v66, v80, v66
	v_cvt_pk_bf16_f32 v67, v81, v67
	global_store_dwordx4 v[72:73], v[64:67], off sc0 sc1
	s_and_saveexec_b64 s[6:7], s[44:45]
	s_cbranch_execz .LBB0_779
	v_lshl_add_u64 v[72:73], v[148:149], 0, s[0:1]
	v_cvt_pk_bf16_f32 v64, v76, v77
	v_cvt_pk_bf16_f32 v65, v78, v79
	v_cvt_pk_bf16_f32 v66, v68, v69
	v_mov_b64_e32 v[68:69], s[54:55]
	v_mad_u64_u32 v[68:69], s[0:1], v72, s25, v[68:69]
	v_mad_i32_i24 v69, v73, s25, v69
	v_lshl_add_u64 v[68:69], v[192:193], 1, v[68:69]
	v_cvt_pk_bf16_f32 v67, v70, v71
	global_store_dwordx4 v[68:69], v[64:67], off sc0 sc1

.LBB0_781:
	s_or_saveexec_b64 s[48:49], s[0:1]
	s_add_i32 s4, s4, 2
	s_ashr_i32 s5, s4, 31
	s_lshl_b64 s[0:1], s[4:5], 2
	s_xor_b64 exec, exec, s[48:49]
	s_cbranch_execz .LBB0_783
	v_or_b32_e32 v69, s0, v176
	v_cvt_pk_bf16_f32 v48, v64, v65
	v_cvt_pk_bf16_f32 v49, v66, v67
	v_cvt_pk_bf16_f32 v50, v56, v57
	v_mov_b64_e32 v[56:57], s[54:55]
	v_cvt_pk_bf16_f32 v51, v58, v59
	v_mad_u64_u32 v[56:57], s[6:7], v69, s25, v[56:57]
	v_mov_b32_e32 v58, 0x1600
	v_mad_i32_i24 v57, s1, v58, v57
	v_lshl_add_u64 v[56:57], v[192:193], 1, v[56:57]
	v_lshl_or_b32 v68, s4, 1, v176
	global_store_dwordx4 v[56:57], v[48:51], off sc0 sc1
	s_nop 1
	v_cvt_pk_bf16_f32 v48, v60, v61
	v_cvt_pk_bf16_f32 v49, v62, v63
	v_cvt_pk_bf16_f32 v50, v54, v55
	v_cvt_pk_bf16_f32 v51, v52, v53
	v_mov_b64_e32 v[52:53], s[56:57]
	v_mad_u64_u32 v[68:69], s[6:7], v68, s25, v[52:53]
	v_mad_i32_i24 v69, s5, v58, v69
.LBB0_783:
	s_or_b64 exec, exec, s[48:49]
	v_lshl_add_u64 v[52:53], v[68:69], 0, v[150:151]
	v_pk_mul_f32 v[44:45], v[44:45], v[206:207] op_sel_hi:[1,0]
	global_store_dwordx4 v[52:53], v[48:51], off sc0 sc1
	ds_bpermute_b32 v48, v173, v44
	ds_bpermute_b32 v49, v175, v44
	v_fma_f32 v44, v140, v44, v128
	ds_bpermute_b32 v50, v173, v45
	ds_bpermute_b32 v53, v175, v45
	s_waitcnt lgkmcnt(3)
	v_cndmask_b32_e64 v58, v48, v83, s[46:47]
	s_waitcnt lgkmcnt(2)
	v_cndmask_b32_e32 v59, v49, v82, vcc
	v_fmac_f32_e32 v44, v136, v58
	v_fmac_f32_e32 v44, v132, v59
	v_mul_f32_e32 v58, 0xbfb8aa3b, v44
	v_exp_f32_e32 v58, v58
	v_pk_mul_f32 v[46:47], v[46:47], v[206:207] op_sel_hi:[1,0]
	ds_bpermute_b32 v52, v173, v46
	s_waitcnt lgkmcnt(2)
	v_cndmask_b32_e64 v59, v50, v80, s[46:47]
	v_fma_f32 v45, v141, v45, v129
	ds_bpermute_b32 v51, v173, v47
	ds_bpermute_b32 v54, v175, v46
	s_waitcnt lgkmcnt(3)
	v_cndmask_b32_e32 v61, v53, v79, vcc
	v_fmac_f32_e32 v45, v137, v59
	ds_bpermute_b32 v55, v175, v47
	v_add_f32_e32 v58, 1.0, v58
	v_fmac_f32_e32 v45, v133, v61
	v_rcp_f32_e32 v58, v58
	v_mul_f32_e32 v59, 0xbfb8aa3b, v45
	v_exp_f32_e32 v59, v59
	s_waitcnt lgkmcnt(3)
	v_cndmask_b32_e64 v57, v52, v84, s[46:47]
	v_fma_f32 v46, v142, v46, v130
	s_waitcnt lgkmcnt(2)
	v_cndmask_b32_e64 v56, v51, v85, s[46:47]
	s_waitcnt lgkmcnt(1)
	v_cndmask_b32_e32 v61, v54, v78, vcc
	v_fmac_f32_e32 v46, v138, v57
	v_fma_f32 v47, v143, v47, v131
	v_pk_mul_f32 v[40:41], v[40:41], v[206:207] op_sel_hi:[1,0]
	s_waitcnt lgkmcnt(0)
	v_cndmask_b32_e32 v60, v55, v81, vcc
	v_mul_f32_e32 v44, v44, v58
	v_fmac_f32_e32 v46, v134, v61
	v_fmac_f32_e32 v47, v139, v56
	v_mul_f32_e32 v40, v40, v44
	v_add_f32_e32 v44, 1.0, v59
	v_mul_f32_e32 v57, 0xbfb8aa3b, v46
	v_fmac_f32_e32 v47, v135, v60
	v_rcp_f32_e32 v44, v44
	v_exp_f32_e32 v57, v57
	v_mul_f32_e32 v56, 0xbfb8aa3b, v47
	v_exp_f32_e32 v56, v56
	v_mul_f32_e32 v44, v45, v44
	v_add_f32_e32 v45, 1.0, v57
	v_rcp_f32_e32 v45, v45
	v_add_f32_e32 v56, 1.0, v56
	v_rcp_f32_e32 v56, v56
	v_pk_mul_f32 v[42:43], v[42:43], v[206:207] op_sel_hi:[1,0]
	v_mul_f32_e32 v41, v41, v44
	v_mul_f32_e32 v44, v46, v45
	v_pk_mul_f32 v[38:39], v[38:39], v[206:207] op_sel_hi:[1,0]
	v_mul_f32_e32 v42, v42, v44
	v_mul_f32_e32 v44, v47, v56
	ds_bpermute_b32 v56, v173, v39
	ds_bpermute_b32 v58, v175, v39
	v_fma_f32 v39, v127, v39, v115
	ds_bpermute_b32 v47, v173, v38
	ds_bpermute_b32 v59, v175, v38
	s_waitcnt lgkmcnt(3)
	v_cndmask_b32_e64 v61, v56, v77, s[46:47]
	s_waitcnt lgkmcnt(2)
	v_cndmask_b32_e32 v63, v58, v75, vcc
	v_fmac_f32_e32 v39, v123, v61
	v_fmac_f32_e32 v39, v119, v63
	v_mul_f32_e32 v61, 0xbfb8aa3b, v39
	v_exp_f32_e32 v61, v61
	v_pk_mul_f32 v[36:37], v[36:37], v[206:207] op_sel_hi:[1,0]
	ds_bpermute_b32 v46, v173, v37
	s_waitcnt lgkmcnt(2)
	v_cndmask_b32_e64 v60, v47, v76, s[46:47]
	v_fma_f32 v38, v126, v38, v114
	v_mul_f32_e32 v43, v43, v44
	ds_bpermute_b32 v44, v173, v36
	ds_bpermute_b32 v57, v175, v37
	s_waitcnt lgkmcnt(3)
	v_cndmask_b32_e32 v64, v59, v73, vcc
	v_fmac_f32_e32 v38, v122, v60
	ds_bpermute_b32 v45, v175, v36
	v_add_f32_e32 v61, 1.0, v61
	v_fmac_f32_e32 v38, v118, v64
	v_rcp_f32_e32 v61, v61
	v_mul_f32_e32 v60, 0xbfb8aa3b, v38
	v_exp_f32_e32 v60, v60
	s_waitcnt lgkmcnt(3)
	v_cndmask_b32_e64 v63, v46, v72, s[46:47]
	v_fma_f32 v37, v125, v37, v113
	s_waitcnt lgkmcnt(2)
	v_cndmask_b32_e64 v62, v44, v74, s[46:47]
	s_waitcnt lgkmcnt(1)
	v_cndmask_b32_e32 v64, v57, v70, vcc
	v_fmac_f32_e32 v37, v121, v63
	v_fma_f32 v36, v124, v36, v112
	v_pk_mul_f32 v[34:35], v[34:35], v[206:207] op_sel_hi:[1,0]
	s_waitcnt lgkmcnt(0)
	v_cndmask_b32_e32 v65, v45, v71, vcc
	v_mul_f32_e32 v39, v39, v61
	v_fmac_f32_e32 v37, v117, v64
	v_fmac_f32_e32 v36, v120, v62
	v_mul_f32_e32 v39, v35, v39
	v_add_f32_e32 v35, 1.0, v60
	v_mul_f32_e32 v60, 0xbfb8aa3b, v37
	v_fmac_f32_e32 v36, v116, v65
	v_rcp_f32_e32 v35, v35
	v_exp_f32_e32 v60, v60
	v_mul_f32_e32 v61, 0xbfb8aa3b, v36
	v_exp_f32_e32 v61, v61
	v_mul_f32_e32 v35, v38, v35
	v_add_f32_e32 v38, 1.0, v60
	v_rcp_f32_e32 v38, v38
	v_add_f32_e32 v60, 1.0, v61
	v_rcp_f32_e32 v60, v60
	v_pk_mul_f32 v[32:33], v[32:33], v[206:207] op_sel_hi:[1,0]
	v_mul_f32_e32 v61, v34, v35
	v_mul_f32_e32 v34, v37, v38
	v_mul_f32_e32 v33, v33, v34
	v_mul_f32_e32 v34, v36, v60
	v_mul_f32_e32 v32, v32, v34
	v_cvt_pk_bf16_f32 v34, v40, v41
	v_cvt_pk_bf16_f32 v35, v42, v43
	v_cvt_pk_bf16_f32 v36, v32, v33
	v_mov_b64_e32 v[32:33], s[52:53]
	v_cvt_pk_bf16_f32 v37, v61, v39
	v_mad_i64_i32 v[38:39], s[4:5], v190, s25, v[32:33]
	v_lshl_add_u64 v[38:39], v[38:39], 0, v[150:151]
	v_pk_mul_f32 v[28:29], v[28:29], v[202:203] op_sel_hi:[1,0]
	global_store_dwordx4 v[38:39], v[34:37], off sc0 sc1
	ds_bpermute_b32 v34, v173, v28
	ds_bpermute_b32 v35, v175, v28
	v_fma_f32 v28, v140, v28, v128
	v_pk_mul_f32 v[30:31], v[30:31], v[202:203] op_sel_hi:[1,0]
	ds_bpermute_b32 v36, v173, v29
	s_waitcnt lgkmcnt(2)
	v_cndmask_b32_e64 v48, v34, v48, s[46:47]
	s_waitcnt lgkmcnt(1)
	v_cndmask_b32_e32 v49, v35, v49, vcc
	v_fmac_f32_e32 v28, v136, v48
	ds_bpermute_b32 v37, v173, v31
	ds_bpermute_b32 v39, v175, v29
	v_fmac_f32_e32 v28, v132, v49
	v_mul_f32_e32 v48, 0xbfb8aa3b, v28
	v_exp_f32_e32 v48, v48
	ds_bpermute_b32 v38, v173, v30
	s_waitcnt lgkmcnt(3)
	v_cndmask_b32_e64 v49, v36, v50, s[46:47]
	v_fma_f32 v29, v141, v29, v129
	ds_bpermute_b32 v40, v175, v30
	s_waitcnt lgkmcnt(3)
	v_cndmask_b32_e64 v42, v37, v51, s[46:47]
	s_waitcnt lgkmcnt(2)
	v_cndmask_b32_e32 v51, v39, v53, vcc
	v_fmac_f32_e32 v29, v137, v49
	ds_bpermute_b32 v41, v175, v31
	v_add_f32_e32 v48, 1.0, v48
	v_fmac_f32_e32 v29, v133, v51
	v_rcp_f32_e32 v48, v48
	v_mul_f32_e32 v49, 0xbfb8aa3b, v29
	v_exp_f32_e32 v49, v49
	s_waitcnt lgkmcnt(2)
	v_cndmask_b32_e64 v43, v38, v52, s[46:47]
	v_fma_f32 v30, v142, v30, v130
	s_waitcnt lgkmcnt(1)
	v_cndmask_b32_e32 v51, v40, v54, vcc
	v_fmac_f32_e32 v30, v138, v43
	v_fma_f32 v31, v143, v31, v131
	v_pk_mul_f32 v[24:25], v[24:25], v[202:203] op_sel_hi:[1,0]
	s_waitcnt lgkmcnt(0)
	v_cndmask_b32_e32 v50, v41, v55, vcc
	v_mul_f32_e32 v28, v28, v48
	v_fmac_f32_e32 v30, v134, v51
	v_fmac_f32_e32 v31, v139, v42
	v_mul_f32_e32 v24, v24, v28
	v_add_f32_e32 v28, 1.0, v49
	v_mul_f32_e32 v43, 0xbfb8aa3b, v30
	v_fmac_f32_e32 v31, v135, v50
	v_rcp_f32_e32 v28, v28
	v_exp_f32_e32 v43, v43
	v_mul_f32_e32 v42, 0xbfb8aa3b, v31
	v_exp_f32_e32 v42, v42
	v_mul_f32_e32 v28, v29, v28
	v_add_f32_e32 v29, 1.0, v43
	v_rcp_f32_e32 v29, v29
	v_add_f32_e32 v42, 1.0, v42
	v_rcp_f32_e32 v42, v42
	v_pk_mul_f32 v[26:27], v[26:27], v[202:203] op_sel_hi:[1,0]
	v_mul_f32_e32 v25, v25, v28
	v_mul_f32_e32 v28, v30, v29
	v_pk_mul_f32 v[22:23], v[22:23], v[202:203] op_sel_hi:[1,0]
	v_mul_f32_e32 v26, v26, v28
	v_mul_f32_e32 v28, v31, v42
	ds_bpermute_b32 v42, v173, v23
	ds_bpermute_b32 v48, v175, v23
	v_fma_f32 v23, v127, v23, v115
	ds_bpermute_b32 v31, v173, v22
	ds_bpermute_b32 v49, v175, v22
	s_waitcnt lgkmcnt(3)
	v_cndmask_b32_e64 v50, v42, v56, s[46:47]
	s_waitcnt lgkmcnt(2)
	v_cndmask_b32_e32 v51, v48, v58, vcc
	v_fmac_f32_e32 v23, v123, v50
	v_fmac_f32_e32 v23, v119, v51
	v_mul_f32_e32 v50, 0xbfb8aa3b, v23
	v_exp_f32_e32 v50, v50
	v_pk_mul_f32 v[20:21], v[20:21], v[202:203] op_sel_hi:[1,0]
	ds_bpermute_b32 v30, v173, v21
	s_waitcnt lgkmcnt(2)
	v_cndmask_b32_e64 v47, v31, v47, s[46:47]
	v_fma_f32 v22, v126, v22, v114
	v_mul_f32_e32 v27, v27, v28
	ds_bpermute_b32 v28, v173, v20
	ds_bpermute_b32 v43, v175, v21
	s_waitcnt lgkmcnt(3)
	v_cndmask_b32_e32 v51, v49, v59, vcc
	v_fmac_f32_e32 v22, v122, v47
	ds_bpermute_b32 v29, v175, v20
	v_add_f32_e32 v50, 1.0, v50
	v_fmac_f32_e32 v22, v118, v51
	v_rcp_f32_e32 v50, v50
	v_mul_f32_e32 v47, 0xbfb8aa3b, v22
	v_exp_f32_e32 v47, v47
	s_waitcnt lgkmcnt(3)
	v_cndmask_b32_e64 v46, v30, v46, s[46:47]
	v_fma_f32 v21, v125, v21, v113
	s_waitcnt lgkmcnt(2)
	v_cndmask_b32_e64 v44, v28, v44, s[46:47]
	s_waitcnt lgkmcnt(1)
	v_cndmask_b32_e32 v51, v43, v57, vcc
	v_fmac_f32_e32 v21, v121, v46
	v_fma_f32 v20, v124, v20, v112
	v_pk_mul_f32 v[18:19], v[18:19], v[202:203] op_sel_hi:[1,0]
	s_waitcnt lgkmcnt(0)
	v_cndmask_b32_e32 v45, v29, v45, vcc
	v_mul_f32_e32 v23, v23, v50
	v_fmac_f32_e32 v21, v117, v51
	v_fmac_f32_e32 v20, v120, v44
	v_mul_f32_e32 v19, v19, v23
	v_add_f32_e32 v23, 1.0, v47
	v_mul_f32_e32 v46, 0xbfb8aa3b, v21
	v_fmac_f32_e32 v20, v116, v45
	v_rcp_f32_e32 v23, v23
	v_exp_f32_e32 v46, v46
	v_mul_f32_e32 v44, 0xbfb8aa3b, v20
	v_exp_f32_e32 v44, v44
	v_mul_f32_e32 v22, v22, v23
	v_add_f32_e32 v23, 1.0, v46
	v_rcp_f32_e32 v23, v23
	v_add_f32_e32 v44, 1.0, v44
	v_rcp_f32_e32 v44, v44
	v_pk_mul_f32 v[16:17], v[16:17], v[202:203] op_sel_hi:[1,0]
	v_mul_f32_e32 v22, v18, v22
	v_mul_f32_e32 v18, v21, v23
	v_mul_f32_e32 v18, v17, v18
	v_mul_f32_e32 v17, v20, v44
	v_mul_f32_e32 v20, v16, v17
	v_cvt_pk_bf16_f32 v16, v24, v25
	v_cvt_pk_bf16_f32 v17, v26, v27
	v_cvt_pk_bf16_f32 v18, v20, v18
	v_mad_i64_i32 v[20:21], s[4:5], v174, s25, v[32:33]
	v_lshl_add_u64 v[20:21], v[20:21], 0, v[150:151]
	v_pk_mul_f32 v[12:13], v[12:13], v[198:199] op_sel_hi:[1,0]
	v_cvt_pk_bf16_f32 v19, v22, v19
	global_store_dwordx4 v[20:21], v[16:19], off sc0 sc1
	ds_bpermute_b32 v16, v173, v12
	ds_bpermute_b32 v17, v175, v12
	v_pk_mul_f32 v[14:15], v[14:15], v[198:199] op_sel_hi:[1,0]
	v_fma_f32 v24, v140, v12, v128
	ds_bpermute_b32 v18, v173, v13
	s_waitcnt lgkmcnt(2)
	v_cndmask_b32_e64 v16, v16, v34, s[46:47]
	ds_bpermute_b32 v23, v175, v15
	s_waitcnt lgkmcnt(2)
	v_cndmask_b32_e32 v17, v17, v35, vcc
	v_fmac_f32_e32 v24, v136, v16
	ds_bpermute_b32 v21, v175, v13
	v_fmac_f32_e32 v24, v132, v17
	v_mul_f32_e32 v16, 0xbfb8aa3b, v24
	v_exp_f32_e32 v16, v16
	s_waitcnt lgkmcnt(2)
	v_cndmask_b32_e64 v17, v18, v36, s[46:47]
	s_waitcnt lgkmcnt(1)
	v_cndmask_b32_e32 v18, v23, v41, vcc
	v_fma_f32 v23, v141, v13, v129
	s_waitcnt lgkmcnt(0)
	v_cndmask_b32_e32 v21, v21, v39, vcc
	v_fmac_f32_e32 v23, v137, v17
	v_add_f32_e32 v16, 1.0, v16
	v_fmac_f32_e32 v23, v133, v21
	ds_bpermute_b32 v20, v173, v14
	v_rcp_f32_e32 v16, v16
	v_mul_f32_e32 v17, 0xbfb8aa3b, v23
	ds_bpermute_b32 v22, v175, v14
	v_exp_f32_e32 v17, v17
	v_pk_mul_f32 v[8:9], v[8:9], v[198:199] op_sel_hi:[1,0]
	v_mul_f32_e32 v16, v24, v16
	s_waitcnt lgkmcnt(1)
	v_cndmask_b32_e64 v20, v20, v38, s[46:47]
	v_mul_f32_e32 v8, v8, v16
	v_add_f32_e32 v16, 1.0, v17
	v_fma_f32 v17, v142, v14, v130
	s_waitcnt lgkmcnt(0)
	v_cndmask_b32_e32 v21, v22, v40, vcc
	v_fmac_f32_e32 v17, v138, v20
	ds_bpermute_b32 v19, v173, v15
	v_fmac_f32_e32 v17, v134, v21
	v_mul_f32_e32 v20, 0xbfb8aa3b, v17
	v_exp_f32_e32 v20, v20
	v_fmac_f32_e32 v131, v143, v15
	s_waitcnt lgkmcnt(0)
	v_cndmask_b32_e64 v19, v19, v37, s[46:47]
	v_pk_mul_f32 v[6:7], v[6:7], v[198:199] op_sel_hi:[1,0]
	v_fmac_f32_e32 v131, v139, v19
	v_add_f32_e32 v19, 1.0, v20
	ds_bpermute_b32 v20, v173, v7
	ds_bpermute_b32 v22, v175, v7
	v_fmac_f32_e32 v131, v135, v18
	v_mul_f32_e32 v18, 0xbfb8aa3b, v131
	v_exp_f32_e32 v18, v18
	s_waitcnt lgkmcnt(1)
	v_cndmask_b32_e64 v20, v20, v42, s[46:47]
	v_fma_f32 v24, v127, v7, v115
	s_waitcnt lgkmcnt(0)
	v_cndmask_b32_e32 v22, v22, v48, vcc
	v_fmac_f32_e32 v24, v123, v20
	v_fmac_f32_e32 v24, v119, v22
	v_rcp_f32_e32 v16, v16
	v_mul_f32_e32 v20, 0xbfb8aa3b, v24
	v_rcp_f32_e32 v19, v19
	v_add_f32_e32 v18, 1.0, v18
	v_exp_f32_e32 v20, v20
	v_rcp_f32_e32 v18, v18
	v_mul_f32_e32 v16, v23, v16
	v_pk_mul_f32 v[10:11], v[10:11], v[198:199] op_sel_hi:[1,0]
	v_mul_f32_e32 v9, v9, v16
	v_mul_f32_e32 v16, v17, v19
	v_pk_mul_f32 v[4:5], v[4:5], v[198:199] op_sel_hi:[1,0]
	ds_bpermute_b32 v19, v173, v6
	ds_bpermute_b32 v23, v175, v6
	v_add_f32_e32 v20, 1.0, v20
	v_mul_f32_e32 v10, v10, v16
	v_mul_f32_e32 v16, v131, v18
	ds_bpermute_b32 v18, v173, v5
	v_rcp_f32_e32 v20, v20
	v_mul_f32_e32 v11, v11, v16
	ds_bpermute_b32 v16, v173, v4
	ds_bpermute_b32 v21, v175, v5
	ds_bpermute_b32 v17, v175, v4
	v_pk_mul_f32 v[2:3], v[2:3], v[198:199] op_sel_hi:[1,0]
	s_waitcnt lgkmcnt(5)
	v_cndmask_b32_e64 v19, v19, v31, s[46:47]
	s_waitcnt lgkmcnt(4)
	v_cndmask_b32_e32 v22, v23, v49, vcc
	v_fma_f32 v23, v126, v6, v114
	v_mul_f32_e32 v20, v24, v20
	s_waitcnt lgkmcnt(3)
	v_cndmask_b32_e64 v18, v18, v30, s[46:47]
	v_fmac_f32_e32 v23, v122, v19
	v_mul_f32_e32 v3, v3, v20
	v_fma_f32 v20, v125, v5, v113
	s_waitcnt lgkmcnt(2)
	v_cndmask_b32_e64 v16, v16, v28, s[46:47]
	v_fmac_f32_e32 v23, v118, v22
	s_waitcnt lgkmcnt(1)
	v_cndmask_b32_e32 v21, v21, v43, vcc
	v_fmac_f32_e32 v20, v121, v18
	v_fmac_f32_e32 v112, v124, v4
	s_waitcnt lgkmcnt(0)
	v_cndmask_b32_e32 v17, v17, v29, vcc
	v_mul_f32_e32 v19, 0xbfb8aa3b, v23
	v_fmac_f32_e32 v20, v117, v21
	v_fmac_f32_e32 v112, v120, v16
	v_exp_f32_e32 v19, v19
	v_mul_f32_e32 v18, 0xbfb8aa3b, v20
	v_fmac_f32_e32 v112, v116, v17
	v_exp_f32_e32 v18, v18
	v_mul_f32_e32 v16, 0xbfb8aa3b, v112
	v_exp_f32_e32 v16, v16
	v_add_f32_e32 v19, 1.0, v19
	v_rcp_f32_e32 v19, v19
	v_add_f32_e32 v18, 1.0, v18
	v_rcp_f32_e32 v18, v18
	v_add_f32_e32 v16, 1.0, v16
	v_rcp_f32_e32 v16, v16
	v_mul_f32_e32 v17, v23, v19
	v_pk_mul_f32 v[0:1], v[0:1], v[198:199] op_sel_hi:[1,0]
	v_mul_f32_e32 v17, v2, v17
	v_mul_f32_e32 v2, v20, v18
	v_mul_f32_e32 v2, v1, v2
	v_mul_f32_e32 v1, v112, v16
	v_mul_f32_e32 v16, v0, v1
	v_cvt_pk_bf16_f32 v0, v8, v9
	v_mad_i64_i32 v[8:9], s[4:5], v172, s25, v[32:33]
	v_lshl_add_u64 v[8:9], v[8:9], 0, v[150:151]
	v_cvt_pk_bf16_f32 v1, v10, v11
	v_cvt_pk_bf16_f32 v2, v16, v2
	v_cvt_pk_bf16_f32 v3, v17, v3
	global_store_dwordx4 v[8:9], v[0:3], off sc0 sc1
	s_and_saveexec_b64 s[4:5], s[44:45]
	s_cbranch_execz .LBB0_785
	v_lshl_add_u64 v[8:9], v[148:149], 0, s[0:1]
	v_cvt_pk_bf16_f32 v0, v12, v13
	v_cvt_pk_bf16_f32 v1, v14, v15
	v_cvt_pk_bf16_f32 v2, v4, v5
	v_mov_b64_e32 v[4:5], s[54:55]
	v_mad_u64_u32 v[4:5], s[0:1], v8, s25, v[4:5]
	v_mad_i32_i24 v5, v9, s25, v5
	v_lshl_add_u64 v[4:5], v[192:193], 1, v[4:5]
	v_cvt_pk_bf16_f32 v3, v6, v7
	global_store_dwordx4 v[4:5], v[0:3], off sc0 sc1
